# out-proj epilogue: all 16 x-loads per half preloaded into dead fragment regs, counted vmcnt, queue shift (on top of rot8)
# speedup vs baseline: 1.0155x; 1.0066x over previous
.Lgemm_621_exit:
	v_mfma_f32_16x16x32_bf16 v[28:31], v[148:151], v[162:165], v[28:31]
	v_mfma_f32_16x16x32_bf16 v[16:19], v[152:155], v[162:165], v[16:19]
	v_mfma_f32_16x16x32_bf16 v[8:11], v[244:247], v[162:165], v[8:11]
	v_mfma_f32_16x16x32_bf16 v[0:3], v[248:251], v[162:165], v[0:3]
	v_mfma_f32_16x16x32_bf16 v[52:55], v[148:151], v[166:169], v[52:55]
	v_mfma_f32_16x16x32_bf16 v[44:47], v[152:155], v[166:169], v[44:47]
	v_mfma_f32_16x16x32_bf16 v[36:39], v[244:247], v[166:169], v[36:39]
	v_mfma_f32_16x16x32_bf16 v[56:59], v[248:251], v[166:169], v[56:59]
	v_mfma_f32_16x16x32_bf16 v[24:27], v[148:151], v[170:173], v[24:27]
	v_mfma_f32_16x16x32_bf16 v[12:15], v[152:155], v[170:173], v[12:15]
	v_mfma_f32_16x16x32_bf16 v[4:7], v[244:247], v[170:173], v[4:7]
	v_mfma_f32_16x16x32_bf16 v[20:23], v[248:251], v[170:173], v[20:23]
	v_add_u32_e32 v157, v137, v140
	ds_read_b128 v[128:131], v157 offset:32768
	v_add_u32_e32 v210, v139, v140
	ds_read_b128 v[148:151], v210 offset:36864
	ds_read_b128 v[152:155], v210 offset:38912
	ds_read_b128 v[140:143], v210 offset:32768
	ds_read_b128 v[144:147], v210 offset:34816
	v_add_u32_e32 v139, v139, v138
	s_lshr_b32 s4, s63, 3
	s_lshl_b32 s60, s62, 21
	s_waitcnt lgkmcnt(2)
	v_mfma_f32_16x16x32_bf16 v[158:161], v[128:131], v[152:155], v[112:115]
	s_lshl_b32 s86, s62, 14
	s_mul_i32 s4, s4, 0xc000
	s_add_u32 s4, s72, s4
	ds_read_b128 v[112:115], v157 offset:34816
	s_waitcnt lgkmcnt(2)
	v_mfma_f32_16x16x32_bf16 v[124:127], v[128:131], v[140:143], v[124:127]
	s_addc_u32 s5, s73, 0
	s_lshl_b64 s[62:63], s[58:59], 2
	s_add_u32 s4, s4, s62
	s_waitcnt lgkmcnt(0)
	v_mfma_f32_16x16x32_bf16 v[162:165], v[112:115], v[140:143], v[108:111]
	s_addc_u32 s5, s5, s63
	s_add_u32 s64, s4, 0x4000
	s_addc_u32 s65, s5, 0
	v_mfma_f32_16x16x32_bf16 v[166:169], v[112:115], v[144:147], v[104:107]
	s_nop 2
	ds_read_b128 v[104:107], v157 offset:38912
	ds_read_b128 v[108:111], v157 offset:36864
	s_add_u32 s66, s46, s62
	s_addc_u32 s67, s47, s63
	s_waitcnt lgkmcnt(0)
	v_mfma_f32_16x16x32_bf16 v[174:177], v[108:111], v[144:147], v[88:91]
	s_lshl_b32 s70, s61, 1
	s_nop 1
	v_add_u32_e32 v88, v137, v138
	s_ashr_i32 s71, s70, 31
	v_mfma_f32_16x16x32_bf16 v[120:123], v[128:131], v[144:147], v[120:123]
	s_add_u32 s68, s4, 0x8000
	s_addc_u32 s69, s5, 0
	s_lshl_b64 s[58:59], s[58:59], 1
	v_mfma_f32_16x16x32_bf16 v[170:173], v[108:111], v[140:143], v[92:95]
	s_mov_b32 s61, s1
	s_lshl_b64 s[70:71], s[70:71], 2
	v_mfma_f32_16x16x32_bf16 v[178:181], v[108:111], v[148:151], v[84:87]
	v_mfma_f32_16x16x32_bf16 v[182:185], v[108:111], v[152:155], v[80:83]
	s_nop 2
	ds_read_b128 v[80:83], v139 offset:51200
	ds_read_b128 v[186:189], v139 offset:49152
	ds_read_b128 v[190:193], v139 offset:38912
	ds_read_b128 v[194:197], v139 offset:36864
	ds_read_b128 v[198:201], v139 offset:34816
	ds_read_b128 v[202:205], v139 offset:32768
	v_mfma_f32_16x16x32_bf16 v[140:143], v[104:107], v[140:143], v[76:79]
	v_mfma_f32_16x16x32_bf16 v[144:147], v[104:107], v[144:147], v[72:75]
	s_nop 2
	ds_read_b128 v[72:75], v88 offset:38912
	ds_read_b128 v[76:79], v88 offset:36864
	ds_read_b128 v[84:87], v88 offset:34816
	ds_read_b128 v[92:95], v88 offset:32768
	v_mfma_f32_16x16x32_bf16 v[116:119], v[128:131], v[148:151], v[116:119]
	v_mfma_f32_16x16x32_bf16 v[100:103], v[112:115], v[148:151], v[100:103]
	v_mfma_f32_16x16x32_bf16 v[96:99], v[112:115], v[152:155], v[96:99]
	s_waitcnt lgkmcnt(0)
	v_mfma_f32_16x16x32_bf16 v[218:221], v[92:95], v[202:205], v[124:127]
	v_mfma_f32_16x16x32_bf16 v[120:123], v[92:95], v[198:201], v[120:123]
	s_nop 1
	v_lshl_or_b32 v126, v132, 2, v136
	v_mad_u32_u24 v124, v134, s9, 0
	v_lshlrev_b32_e32 v125, 2, v135
	v_mfma_f32_16x16x32_bf16 v[116:119], v[92:95], v[194:197], v[116:119]
	v_mul_lo_u32 v126, v126, s14
	v_add3_u32 v126, v124, v125, v126
	v_add_u32_e32 v127, 0x400, v126
	v_mfma_f32_16x16x32_bf16 v[134:137], v[92:95], v[190:193], v[158:161]
	v_add_u32_e32 v138, 0x4800, v126
	v_mov_b32_e32 v125, v156
	v_mfma_f32_16x16x32_bf16 v[148:151], v[104:107], v[148:151], v[68:71]
	s_nop 2
	ds_read_b128 v[68:71], v210 offset:55296
	ds_read_b128 v[206:209], v210 offset:53248
	ds_read_b128 v[88:91], v210 offset:51200
	ds_read_b128 v[210:213], v210 offset:49152
	v_mfma_f32_16x16x32_bf16 v[152:155], v[104:107], v[152:155], v[64:67]
	ds_read_b128 v[214:217], v139 offset:53248
	s_nop 1
	ds_read_b128 v[64:67], v139 offset:55296
	s_waitcnt vmcnt(0)
	s_waitcnt lgkmcnt(0)
	s_barrier
	ds_write2_b32 v126, v218, v120 offset1:16
	ds_write2_b32 v126, v219, v121 offset0:136 offset1:152
	ds_write2_b32 v127, v220, v122 offset0:16 offset1:32
	v_mfma_f32_16x16x32_bf16 v[158:161], v[84:87], v[202:205], v[162:165]
	ds_write2_b32 v127, v221, v123 offset0:152 offset1:168
	ds_write2_b32 v126, v116, v134 offset0:32 offset1:48
	ds_write2_b32 v126, v117, v135 offset0:168 offset1:184
	ds_write2_b32 v127, v118, v136 offset0:48 offset1:64
	ds_write2_b32 v127, v119, v137 offset0:184 offset1:200
	v_add_u32_e32 v134, 0x2000, v126
	v_mfma_f32_16x16x32_bf16 v[120:123], v[84:87], v[198:201], v[166:169]
	v_add_u32_e32 v135, 0x2400, v126
	v_add_u32_e32 v136, 0x2800, v126
	v_add_u32_e32 v137, 0x4400, v126
	v_mfma_f32_16x16x32_bf16 v[100:103], v[84:87], v[194:197], v[100:103]
	v_add_u32_e32 v139, 0x6400, v126
	s_nop 2
	ds_write2_b32 v134, v158, v120 offset0:128 offset1:144
	ds_write2_b32 v135, v159, v121 offset0:8 offset1:24
	v_mfma_f32_16x16x32_bf16 v[96:99], v[84:87], v[190:193], v[96:99]
	ds_write2_b32 v135, v160, v122 offset0:144 offset1:160
	ds_write2_b32 v136, v161, v123 offset0:24 offset1:40
	s_nop 5
	ds_write2_b32 v134, v100, v96 offset0:160 offset1:176
	ds_write2_b32 v135, v101, v97 offset0:40 offset1:56
	ds_write2_b32 v135, v102, v98 offset0:176 offset1:192
	v_mfma_f32_16x16x32_bf16 v[116:119], v[76:79], v[202:205], v[170:173]
	ds_write2_b32 v136, v103, v99 offset0:56 offset1:72
	v_mfma_f32_16x16x32_bf16 v[120:123], v[76:79], v[198:201], v[174:177]
	v_mfma_f32_16x16x32_bf16 v[96:99], v[76:79], v[194:197], v[178:181]
	v_mfma_f32_16x16x32_bf16 v[100:103], v[76:79], v[190:193], v[182:185]
	s_nop 5
	ds_write2_b32 v137, v116, v120 offset1:16
	ds_write2_b32 v137, v117, v121 offset0:136 offset1:152
	ds_write2_b32 v138, v118, v122 offset0:16 offset1:32
	ds_write2_b32 v138, v119, v123 offset0:152 offset1:168
	ds_write2_b32 v137, v96, v100 offset0:32 offset1:48
	ds_write2_b32 v137, v97, v101 offset0:168 offset1:184
	v_mfma_f32_16x16x32_bf16 v[116:119], v[72:75], v[202:205], v[140:143]
	ds_write2_b32 v138, v98, v102 offset0:48 offset1:64
	ds_write2_b32 v138, v99, v103 offset0:184 offset1:200
	s_nop 0
	v_add_u32_e32 v140, 0x6800, v126
	v_mfma_f32_16x16x32_bf16 v[96:99], v[72:75], v[198:201], v[144:147]
	v_add_u32_e32 v141, 0x6c00, v126
	v_mfma_f32_16x16x32_bf16 v[100:103], v[72:75], v[194:197], v[148:151]
	v_mfma_f32_16x16x32_bf16 v[60:63], v[128:131], v[210:213], v[60:63]
	s_nop 4
	ds_write2_b32 v139, v116, v96 offset0:128 offset1:144
	ds_write2_b32 v140, v117, v97 offset0:8 offset1:24
	ds_write2_b32 v140, v118, v98 offset0:144 offset1:160
	ds_write2_b32 v141, v119, v99 offset0:24 offset1:40
	v_mfma_f32_16x16x32_bf16 v[96:99], v[72:75], v[190:193], v[152:155]
	s_nop 7
	ds_write2_b32 v139, v100, v96 offset0:160 offset1:176
	ds_write2_b32 v140, v101, v97 offset0:40 offset1:56
	ds_write2_b32 v140, v102, v98 offset0:176 offset1:192
	ds_write2_b32 v141, v103, v99 offset0:56 offset1:72
	s_waitcnt lgkmcnt(0)
	s_barrier
	v_mfma_f32_16x16x32_bf16 v[100:103], v[128:131], v[206:209], v[52:55]
	v_and_b32_e32 v132, 31, v125
	v_lshlrev_b32_e32 v124, 4, v132
	s_nop 0
	global_load_dwordx4 v[52:55], v124, s[68:69]
	global_load_dwordx4 v[116:119], v124, s[66:67]
	global_load_dwordx4 v[96:99], v124, s[64:65]
	v_ashrrev_i32_e32 v146, 5, v125
	v_ashrrev_i32_e32 v147, 31, v146
	v_cmp_eq_u32_e64 s[4:5], 0, v132
	v_mfma_f32_16x16x32_bf16 v[120:123], v[104:107], v[206:209], v[56:59]
	v_lshlrev_b32_e32 v132, 3, v132
	s_waitcnt vmcnt(2)
	v_add_f32_e32 v52, 1.0, v52
	s_waitcnt vmcnt(1)
	v_mul_f32_e32 v142, v116, v52
	v_add_f32_e32 v52, 1.0, v53
	v_mul_f32_e32 v143, v117, v52
	v_add_f32_e32 v52, 1.0, v54
	v_mul_f32_e32 v144, v118, v52
	v_add_f32_e32 v52, 1.0, v55
	v_mul_f32_e32 v145, v119, v52
	v_lshlrev_b64 v[52:53], 12, v[146:147]
	v_lshl_add_u64 v[56:57], s[0:1], 0, v[52:53]
	v_mfma_f32_16x16x32_bf16 v[44:47], v[112:115], v[206:209], v[44:47]
	v_mfma_f32_16x16x32_bf16 v[52:55], v[92:95], v[186:189], v[60:63]
	s_nop 2
	v_lshl_add_u64 v[60:61], v[56:57], 0, v[132:133]
	v_mfma_f32_16x16x32_bf16 v[56:59], v[92:95], v[214:217], v[100:103]
	s_nop 2
	v_lshl_add_u64 v[100:101], v[60:61], 0, s[58:59]
	v_lshlrev_b64 v[60:61], 13, v[146:147]
	v_lshl_add_u64 v[60:61], s[60:61], 0, v[60:61]
	v_or_b32_e32 v60, v60, v124
	v_lshl_add_u64 v[116:117], v[60:61], 0, s[62:63]
	v_mfma_f32_16x16x32_bf16 v[60:63], v[84:87], v[214:217], v[44:47]
	v_lshl_add_u64 v[102:103], s[30:31], 0, v[116:117]
	v_lshl_add_u64 v[116:117], s[52:53], 0, v[116:117]
	s_nop 0
	v_mad_u64_u32 v[44:45], s[76:77], v146, s14, v[124:125]
	v_mfma_f32_16x16x32_bf16 v[48:51], v[112:115], v[210:213], v[48:51]
	s_add_u32 s76, s86, s70
	s_addc_u32 s77, 0, s71
	v_and_b32_e32 v45, 16, v125
	v_mfma_f32_16x16x32_bf16 v[40:43], v[108:111], v[210:213], v[40:43]
	s_add_u32 s76, s76, 0x1a290800
	v_add3_u32 v132, v44, v45, 0
	v_lshlrev_b64 v[44:45], 6, v[146:147]
	v_mfma_f32_16x16x32_bf16 v[36:39], v[108:111], v[206:209], v[36:39]
	s_addc_u32 s77, s77, 0
	v_lshl_add_u64 v[118:119], s[76:77], 0, v[44:45]
	s_mov_b64 s[76:77], 0
	v_mfma_f32_16x16x32_bf16 v[32:35], v[104:107], v[210:213], v[32:35]
	v_mfma_f32_16x16x32_bf16 v[48:51], v[84:87], v[186:189], v[48:51]
	v_mfma_f32_16x16x32_bf16 v[40:43], v[76:79], v[186:189], v[40:43]
	v_mfma_f32_16x16x32_bf16 v[36:39], v[76:79], v[214:217], v[36:39]
	v_mfma_f32_16x16x32_bf16 v[32:35], v[72:75], v[186:189], v[32:35]
	v_mfma_f32_16x16x32_bf16 v[44:47], v[72:75], v[214:217], v[120:123]
	global_load_dwordx4 v[146:149], v[116:117], off nt
	v_add_co_u32_e32 v244, vcc, 0x20000, v116
	s_nop 1
	v_addc_co_u32_e32 v245, vcc, 0, v117, vcc
	global_load_dwordx4 v[244:247], v[244:245], off nt
	v_add_co_u32_e32 v248, vcc, 0x40000, v116
	s_nop 1
	v_addc_co_u32_e32 v249, vcc, 0, v117, vcc
	global_load_dwordx4 v[248:251], v[248:249], off nt
	v_add_co_u32_e32 v252, vcc, 0x60000, v116
	s_nop 1
	v_addc_co_u32_e32 v253, vcc, 0, v117, vcc
	global_load_dwordx4 v[252:255], v[252:253], off nt
	v_add_co_u32_e32 v160, vcc, 0x80000, v116
	s_nop 1
	v_addc_co_u32_e32 v161, vcc, 0, v117, vcc
	global_load_dwordx4 v[160:163], v[160:161], off nt
	v_add_co_u32_e32 v164, vcc, 0xa0000, v116
	s_nop 1
	v_addc_co_u32_e32 v165, vcc, 0, v117, vcc
	global_load_dwordx4 v[164:167], v[164:165], off nt
	v_add_co_u32_e32 v168, vcc, 0xc0000, v116
	s_nop 1
	v_addc_co_u32_e32 v169, vcc, 0, v117, vcc
	global_load_dwordx4 v[168:171], v[168:169], off nt
	v_add_co_u32_e32 v172, vcc, 0xe0000, v116
	s_nop 1
	v_addc_co_u32_e32 v173, vcc, 0, v117, vcc
	global_load_dwordx4 v[172:175], v[172:173], off nt
	v_add_co_u32_e32 v176, vcc, 0x100000, v116
	s_nop 1
	v_addc_co_u32_e32 v177, vcc, 0, v117, vcc
	global_load_dwordx4 v[176:179], v[176:177], off nt
	v_add_co_u32_e32 v180, vcc, 0x120000, v116
	s_nop 1
	v_addc_co_u32_e32 v181, vcc, 0, v117, vcc
	global_load_dwordx4 v[180:183], v[180:181], off nt
	v_add_co_u32_e32 v184, vcc, 0x140000, v116
	s_nop 1
	v_addc_co_u32_e32 v185, vcc, 0, v117, vcc
	global_load_dwordx4 v[184:187], v[184:185], off nt
	v_add_co_u32_e32 v188, vcc, 0x160000, v116
	s_nop 1
	v_addc_co_u32_e32 v189, vcc, 0, v117, vcc
	global_load_dwordx4 v[188:191], v[188:189], off nt
	v_add_co_u32_e32 v192, vcc, 0x180000, v116
	s_nop 1
	v_addc_co_u32_e32 v193, vcc, 0, v117, vcc
	global_load_dwordx4 v[192:195], v[192:193], off nt
	v_add_co_u32_e32 v196, vcc, 0x1a0000, v116
	s_nop 1
	v_addc_co_u32_e32 v197, vcc, 0, v117, vcc
	global_load_dwordx4 v[196:199], v[196:197], off nt
	v_add_co_u32_e32 v200, vcc, 0x1c0000, v116
	s_nop 1
	v_addc_co_u32_e32 v201, vcc, 0, v117, vcc
	global_load_dwordx4 v[200:203], v[200:201], off nt
	v_add_co_u32_e32 v204, vcc, 0x1e0000, v116
	s_nop 1
	v_addc_co_u32_e32 v205, vcc, 0, v117, vcc
	global_load_dwordx4 v[204:207], v[204:205], off nt
	s_branch .LBB0_624
.LBB0_623:
	s_or_b64 exec, exec, s[78:79]
	s_waitcnt vmcnt(12)
	v_mov_b64_e32 v[146:147], v[160:161]
	v_mov_b64_e32 v[148:149], v[162:163]
	v_mov_b64_e32 v[244:245], v[164:165]
	v_mov_b64_e32 v[246:247], v[166:167]
	v_mov_b64_e32 v[248:249], v[168:169]
	v_mov_b64_e32 v[250:251], v[170:171]
	v_mov_b64_e32 v[252:253], v[172:173]
	v_mov_b64_e32 v[254:255], v[174:175]
	v_mov_b64_e32 v[160:161], v[176:177]
	v_mov_b64_e32 v[162:163], v[178:179]
	v_mov_b64_e32 v[164:165], v[180:181]
	v_mov_b64_e32 v[166:167], v[182:183]
	v_mov_b64_e32 v[168:169], v[184:185]
	v_mov_b64_e32 v[170:171], v[186:187]
	v_mov_b64_e32 v[172:173], v[188:189]
	v_mov_b64_e32 v[174:175], v[190:191]
	v_mov_b64_e32 v[176:177], v[192:193]
	v_mov_b64_e32 v[178:179], v[194:195]
	v_mov_b64_e32 v[180:181], v[196:197]
	v_mov_b64_e32 v[182:183], v[198:199]
	v_mov_b64_e32 v[184:185], v[200:201]
	v_mov_b64_e32 v[186:187], v[202:203]
	v_mov_b64_e32 v[188:189], v[204:205]
	v_mov_b64_e32 v[190:191], v[206:207]
	s_add_u32 s76, s76, 0x80000
	s_addc_u32 s77, s77, 0
	v_lshl_add_u64 v[100:101], v[100:101], 0, s[6:7]
	v_add_u32_e32 v132, 0x8800, v132
	s_cmp_lg_u32 s76, 0x200000
	v_lshl_add_u64 v[118:119], v[118:119], 0, s[56:57]
	s_cbranch_scc0 .LBB0_632
.LBB0_624:
	v_lshl_add_u64 v[124:125], v[116:117], 0, s[76:77]
	ds_read_b128 v[150:153], v132
	v_lshl_add_u64 v[122:123], v[102:103], 0, s[76:77]
	v_lshl_add_u64 v[120:121], s[72:73], 0, v[100:101]
	v_add_co_u32_e32 v154, vcc, s15, v120
	s_waitcnt vmcnt(15) lgkmcnt(0)
	v_pk_fma_f32 v[148:149], v[98:99], v[152:153], v[148:149]
	v_pk_fma_f32 v[146:147], v[96:97], v[150:151], v[146:147]
	global_store_dwordx4 v[122:123], v[146:149], off
	v_mul_f32_e32 v150, v142, v146
	v_mul_f32_e32 v151, v143, v147
	v_pk_mul_f32 v[146:147], v[146:147], v[146:147]
	v_mul_f32_e32 v152, v144, v148
	v_mul_f32_e32 v153, v145, v149
	v_pk_mul_f32 v[148:149], v[148:149], v[148:149]
	v_add_f32_e32 v146, v146, v147
	v_add_f32_e32 v146, v148, v146
	v_add_f32_e32 v146, v149, v146
	v_addc_co_u32_e32 v155, vcc, 0, v121, vcc
	s_nop 0
	v_add_f32_dpp v146, v146, v146 quad_perm:[1,0,3,2] row_mask:0xf bank_mask:0xf bound_ctrl:1
	v_cvt_pk_bf16_f32 v150, v150, v151
	v_cvt_pk_bf16_f32 v151, v152, v153
	global_store_dwordx2 v[154:155], v[150:151], off
	s_nop 0
	v_add_f32_dpp v146, v146, v146 quad_perm:[2,3,0,1] row_mask:0xf bank_mask:0xf bound_ctrl:1
	s_nop 1
	v_add_f32_dpp v146, v146, v146 row_half_mirror row_mask:0xf bank_mask:0xf bound_ctrl:1
	s_nop 1
	v_add_f32_dpp v146, v146, v146 row_mirror row_mask:0xf bank_mask:0xf bound_ctrl:1
	v_mov_b32_e32 v147, v146
	s_nop 1
	v_permlane16_swap_b32_e32 v146, v147
	s_and_saveexec_b64 s[78:79], s[4:5]
	s_cbranch_execz .LBB0_626
	v_lshl_add_u64 v[148:149], s[72:73], 0, v[118:119]
	v_add_f32_e32 v146, v146, v147
	global_store_dword v[148:149], v146, off offset:-2048
.LBB0_626:
	s_or_b64 exec, exec, s[78:79]
	ds_read_b128 v[150:153], v132 offset:8704
	s_nop 0
	v_add_co_u32_e32 v154, vcc, s22, v122
	s_waitcnt vmcnt(17) lgkmcnt(0)
	v_pk_fma_f32 v[246:247], v[98:99], v[152:153], v[246:247]
	v_addc_co_u32_e32 v155, vcc, 0, v123, vcc
	v_pk_fma_f32 v[244:245], v[96:97], v[150:151], v[244:245]
	global_store_dwordx4 v[154:155], v[244:247], off
	v_mul_f32_e32 v150, v142, v244
	v_mul_f32_e32 v151, v143, v245
	v_pk_mul_f32 v[244:245], v[244:245], v[244:245]
	v_mul_f32_e32 v152, v144, v246
	v_mul_f32_e32 v153, v145, v247
	v_pk_mul_f32 v[246:247], v[246:247], v[246:247]
	v_add_f32_e32 v244, v244, v245
	v_add_f32_e32 v244, v246, v244
	v_add_f32_e32 v244, v247, v244
	v_add_co_u32_e32 v158, vcc, s33, v120
	s_nop 0
	v_add_f32_dpp v244, v244, v244 quad_perm:[1,0,3,2] row_mask:0xf bank_mask:0xf bound_ctrl:1
	v_addc_co_u32_e32 v159, vcc, 0, v121, vcc
	s_nop 0
	v_add_f32_dpp v244, v244, v244 quad_perm:[2,3,0,1] row_mask:0xf bank_mask:0xf bound_ctrl:1
	v_cvt_pk_bf16_f32 v150, v150, v151
	v_cvt_pk_bf16_f32 v151, v152, v153
	global_store_dwordx2 v[158:159], v[150:151], off
	s_nop 0
	v_add_f32_dpp v244, v244, v244 row_half_mirror row_mask:0xf bank_mask:0xf bound_ctrl:1
	s_nop 1
	v_add_f32_dpp v244, v244, v244 row_mirror row_mask:0xf bank_mask:0xf bound_ctrl:1
	v_mov_b32_e32 v245, v244
	s_nop 1
	v_permlane16_swap_b32_e32 v244, v245
	s_and_saveexec_b64 s[78:79], s[4:5]
	s_cbranch_execz .LBB0_628
	v_lshl_add_u64 v[246:247], s[72:73], 0, v[118:119]
	v_add_f32_e32 v244, v244, v245
	global_store_dword v[246:247], v244, off offset:-1024
.LBB0_628:
	s_or_b64 exec, exec, s[78:79]
	ds_read_b128 v[150:153], v132 offset:17408
	s_nop 0
	v_add_co_u32_e32 v154, vcc, s80, v122
	s_waitcnt vmcnt(19) lgkmcnt(0)
	v_pk_fma_f32 v[250:251], v[98:99], v[152:153], v[250:251]
	v_addc_co_u32_e32 v155, vcc, 0, v123, vcc
	v_pk_fma_f32 v[248:249], v[96:97], v[150:151], v[248:249]
	global_store_dwordx4 v[154:155], v[248:251], off
	v_mul_f32_e32 v150, v142, v248
	v_mul_f32_e32 v151, v143, v249
	v_pk_mul_f32 v[248:249], v[248:249], v[248:249]
	v_mul_f32_e32 v152, v144, v250
	v_mul_f32_e32 v153, v145, v251
	v_pk_mul_f32 v[250:251], v[250:251], v[250:251]
	v_add_f32_e32 v248, v248, v249
	v_add_f32_e32 v248, v250, v248
	v_add_f32_e32 v248, v251, v248
	v_add_co_u32_e32 v158, vcc, s81, v120
	s_nop 0
	v_add_f32_dpp v248, v248, v248 quad_perm:[1,0,3,2] row_mask:0xf bank_mask:0xf bound_ctrl:1
	v_addc_co_u32_e32 v159, vcc, 0, v121, vcc
	s_nop 0
	v_add_f32_dpp v248, v248, v248 quad_perm:[2,3,0,1] row_mask:0xf bank_mask:0xf bound_ctrl:1
	v_cvt_pk_bf16_f32 v150, v150, v151
	v_cvt_pk_bf16_f32 v151, v152, v153
	global_store_dwordx2 v[158:159], v[150:151], off
	s_nop 0
	v_add_f32_dpp v248, v248, v248 row_half_mirror row_mask:0xf bank_mask:0xf bound_ctrl:1
	s_nop 1
	v_add_f32_dpp v248, v248, v248 row_mirror row_mask:0xf bank_mask:0xf bound_ctrl:1
	v_mov_b32_e32 v249, v248
	s_nop 1
	v_permlane16_swap_b32_e32 v248, v249
	s_and_saveexec_b64 s[78:79], s[4:5]
	s_cbranch_execz .LBB0_630
	v_lshl_add_u64 v[250:251], s[72:73], 0, v[118:119]
	v_add_f32_e32 v248, v248, v249
	global_store_dword v[250:251], v248, off
.LBB0_630:
	s_or_b64 exec, exec, s[78:79]
	ds_read_b128 v[150:153], v132 offset:26112
	s_nop 0
	v_add_co_u32_e32 v124, vcc, s82, v122
	s_nop 1
	v_addc_co_u32_e32 v125, vcc, 0, v123, vcc
	v_add_co_u32_e32 v154, vcc, s83, v120
	s_waitcnt vmcnt(21) lgkmcnt(0)
	v_pk_fma_f32 v[122:123], v[98:99], v[152:153], v[254:255]
	v_addc_co_u32_e32 v155, vcc, 0, v121, vcc
	v_pk_fma_f32 v[120:121], v[96:97], v[150:151], v[252:253]
	global_store_dwordx4 v[124:125], v[120:123], off
	v_mul_f32_e32 v124, v142, v120
	v_mul_f32_e32 v125, v143, v121
	v_pk_mul_f32 v[120:121], v[120:121], v[120:121]
	v_mul_f32_e32 v252, v144, v122
	v_mul_f32_e32 v253, v145, v123
	v_pk_mul_f32 v[122:123], v[122:123], v[122:123]
	v_add_f32_e32 v120, v120, v121
	v_add_f32_e32 v120, v122, v120
	v_add_f32_e32 v120, v123, v120
	v_cvt_pk_bf16_f32 v124, v124, v125
	v_cvt_pk_bf16_f32 v125, v252, v253
	global_store_dwordx2 v[154:155], v[124:125], off
	s_nop 0
	v_add_f32_dpp v120, v120, v120 quad_perm:[1,0,3,2] row_mask:0xf bank_mask:0xf bound_ctrl:1
	s_nop 1
	v_add_f32_dpp v120, v120, v120 quad_perm:[2,3,0,1] row_mask:0xf bank_mask:0xf bound_ctrl:1
	s_nop 1
	v_add_f32_dpp v120, v120, v120 row_half_mirror row_mask:0xf bank_mask:0xf bound_ctrl:1
	s_nop 1
	v_add_f32_dpp v120, v120, v120 row_mirror row_mask:0xf bank_mask:0xf bound_ctrl:1
	v_mov_b32_e32 v121, v120
	s_nop 1
	v_permlane16_swap_b32_e32 v120, v121
	s_and_saveexec_b64 s[78:79], s[4:5]
	s_cbranch_execz .LBB0_623
	v_lshl_add_u64 v[122:123], s[72:73], 0, v[118:119]
	v_add_f32_e32 v120, v120, v121
	global_store_dword v[122:123], v120, off offset:1024
	s_branch .LBB0_623
.LBB0_632:
	v_mfma_f32_16x16x32_bf16 v[28:31], v[128:131], v[88:91], v[28:31]
	s_barrier
	v_mfma_f32_16x16x32_bf16 v[24:27], v[128:131], v[68:71], v[24:27]
	s_add_u32 s4, s86, s70
	s_addc_u32 s5, 0, s71
	v_mfma_f32_16x16x32_bf16 v[16:19], v[112:115], v[88:91], v[16:19]
	v_mfma_f32_16x16x32_bf16 v[12:15], v[112:115], v[68:71], v[12:15]
	v_mfma_f32_16x16x32_bf16 v[8:11], v[108:111], v[88:91], v[8:11]
	v_mfma_f32_16x16x32_bf16 v[4:7], v[108:111], v[68:71], v[4:7]
	v_mfma_f32_16x16x32_bf16 v[0:3], v[104:107], v[88:91], v[0:3]
	v_mfma_f32_16x16x32_bf16 v[28:31], v[92:95], v[80:83], v[28:31]
	v_mfma_f32_16x16x32_bf16 v[24:27], v[92:95], v[64:67], v[24:27]
	v_mfma_f32_16x16x32_bf16 v[16:19], v[84:87], v[80:83], v[16:19]
	s_nop 5
	ds_write2_b32 v126, v52, v28 offset1:16
	ds_write2_b32 v126, v53, v29 offset0:136 offset1:152
	ds_write2_b32 v127, v54, v30 offset0:16 offset1:32
	ds_write2_b32 v127, v55, v31 offset0:152 offset1:168
	ds_write2_b32 v126, v56, v24 offset0:32 offset1:48
	ds_write2_b32 v126, v57, v25 offset0:168 offset1:184
	ds_write2_b32 v127, v58, v26 offset0:48 offset1:64
	v_mfma_f32_16x16x32_bf16 v[12:15], v[84:87], v[64:67], v[12:15]
	ds_write2_b32 v127, v59, v27 offset0:184 offset1:200
	ds_write2_b32 v134, v48, v16 offset0:128 offset1:144
	ds_write2_b32 v135, v49, v17 offset0:8 offset1:24
	ds_write2_b32 v135, v50, v18 offset0:144 offset1:160
	ds_write2_b32 v136, v51, v19 offset0:24 offset1:40
	s_nop 2
	ds_write2_b32 v134, v60, v12 offset0:160 offset1:176
	ds_write2_b32 v135, v61, v13 offset0:40 offset1:56
	ds_write2_b32 v135, v62, v14 offset0:176 offset1:192
	ds_write2_b32 v136, v63, v15 offset0:56 offset1:72
	v_mfma_f32_16x16x32_bf16 v[8:11], v[76:79], v[80:83], v[8:11]
	s_nop 7
	ds_write2_b32 v137, v40, v8 offset1:16
	ds_write2_b32 v137, v41, v9 offset0:136 offset1:152
	ds_write2_b32 v138, v42, v10 offset0:16 offset1:32
	v_mfma_f32_16x16x32_bf16 v[4:7], v[76:79], v[64:67], v[4:7]
	ds_write2_b32 v138, v43, v11 offset0:152 offset1:168
	s_nop 6
	ds_write2_b32 v137, v36, v4 offset0:32 offset1:48
	ds_write2_b32 v137, v37, v5 offset0:168 offset1:184
	v_mfma_f32_16x16x32_bf16 v[0:3], v[72:75], v[80:83], v[0:3]
	ds_write2_b32 v138, v38, v6 offset0:48 offset1:64
	ds_write2_b32 v138, v39, v7 offset0:184 offset1:200
	s_nop 5
	ds_write2_b32 v139, v32, v0 offset0:128 offset1:144
	ds_write2_b32 v140, v33, v1 offset0:8 offset1:24
	ds_write2_b32 v140, v34, v2 offset0:144 offset1:160
	ds_write2_b32 v141, v35, v3 offset0:24 offset1:40
	v_mfma_f32_16x16x32_bf16 v[4:7], v[104:107], v[68:71], v[20:23]
	v_mfma_f32_16x16x32_bf16 v[0:3], v[72:75], v[64:67], v[4:7]
	s_nop 7
	ds_write2_b32 v139, v44, v0 offset0:160 offset1:176
	ds_write2_b32 v140, v45, v1 offset0:40 offset1:56
	ds_write2_b32 v140, v46, v2 offset0:176 offset1:192
	ds_write2_b32 v141, v47, v3 offset0:56 offset1:72
	v_mov_b32_e32 v4, v156
	s_waitcnt lgkmcnt(0)
	s_barrier
	v_mov_b32_e32 v5, v133
	v_and_b32_e32 v8, 31, v4
	v_lshlrev_b32_e32 v132, 4, v8
	global_load_dwordx4 v[10:13], v132, s[68:69] offset:512
	global_load_dwordx4 v[14:17], v132, s[66:67] offset:512
	global_load_dwordx4 v[0:3], v132, s[64:65] offset:512
	v_ashrrev_i32_e32 v6, 5, v4
	s_add_u32 s64, s4, 0x1a290804
	v_ashrrev_i32_e32 v7, 31, v6
	s_addc_u32 s65, s5, 0
	v_and_b32_e32 v22, 16, v4
	v_cmp_eq_u32_e64 s[4:5], 0, v8
	v_lshlrev_b32_e32 v4, 3, v8
	v_lshlrev_b64 v[8:9], 13, v[6:7]
	v_lshlrev_b64 v[18:19], 12, v[6:7]
	v_mad_u64_u32 v[20:21], s[66:67], v6, s14, v[132:133]
	v_lshlrev_b64 v[24:25], 6, v[6:7]
	v_lshl_add_u64 v[6:7], s[60:61], 0, v[8:9]
	v_lshl_add_u64 v[8:9], s[0:1], 0, v[18:19]
	v_lshl_add_u64 v[6:7], v[6:7], 0, v[132:133]
	v_lshl_add_u64 v[4:5], v[8:9], 0, v[4:5]
	v_lshl_add_u64 v[8:9], v[6:7], 0, s[62:63]
	v_add3_u32 v18, v20, v22, 0
	v_lshl_add_u64 v[4:5], v[4:5], 0, s[58:59]
	v_lshl_add_u64 v[6:7], s[52:53], 0, v[8:9]
	v_lshl_add_u64 v[8:9], s[30:31], 0, v[8:9]
	s_mov_b64 s[58:59], 0
	s_waitcnt vmcnt(2)
	v_add_f32_e32 v10, 1.0, v10
	v_add_f32_e32 v11, 1.0, v11
	v_add_f32_e32 v12, 1.0, v12
	v_add_f32_e32 v13, 1.0, v13
	s_waitcnt vmcnt(1)
	v_mul_f32_e32 v19, v14, v10
	v_mul_f32_e32 v20, v15, v11
	v_mul_f32_e32 v21, v16, v12
	v_mul_f32_e32 v22, v17, v13
	v_lshl_add_u64 v[10:11], s[64:65], 0, v[24:25]
	global_load_dwordx4 v[24:27], v[6:7], off offset:512 nt
	v_add_co_u32_e32 v244, vcc, 0x20000, v6
	s_nop 1
	v_addc_co_u32_e32 v245, vcc, 0, v7, vcc
	global_load_dwordx4 v[244:247], v[244:245], off offset:512 nt
	v_add_co_u32_e32 v248, vcc, 0x40000, v6
	s_nop 1
	v_addc_co_u32_e32 v249, vcc, 0, v7, vcc
	global_load_dwordx4 v[248:251], v[248:249], off offset:512 nt
	v_add_co_u32_e32 v252, vcc, 0x60000, v6
	s_nop 1
	v_addc_co_u32_e32 v253, vcc, 0, v7, vcc
	global_load_dwordx4 v[252:255], v[252:253], off offset:512 nt
	v_add_co_u32_e32 v160, vcc, 0x80000, v6
	s_nop 1
	v_addc_co_u32_e32 v161, vcc, 0, v7, vcc
	global_load_dwordx4 v[160:163], v[160:161], off offset:512 nt
	v_add_co_u32_e32 v164, vcc, 0xa0000, v6
	s_nop 1
	v_addc_co_u32_e32 v165, vcc, 0, v7, vcc
	global_load_dwordx4 v[164:167], v[164:165], off offset:512 nt
	v_add_co_u32_e32 v168, vcc, 0xc0000, v6
	s_nop 1
	v_addc_co_u32_e32 v169, vcc, 0, v7, vcc
	global_load_dwordx4 v[168:171], v[168:169], off offset:512 nt
	v_add_co_u32_e32 v172, vcc, 0xe0000, v6
	s_nop 1
	v_addc_co_u32_e32 v173, vcc, 0, v7, vcc
	global_load_dwordx4 v[172:175], v[172:173], off offset:512 nt
	v_add_co_u32_e32 v176, vcc, 0x100000, v6
	s_nop 1
	v_addc_co_u32_e32 v177, vcc, 0, v7, vcc
	global_load_dwordx4 v[176:179], v[176:177], off offset:512 nt
	v_add_co_u32_e32 v180, vcc, 0x120000, v6
	s_nop 1
	v_addc_co_u32_e32 v181, vcc, 0, v7, vcc
	global_load_dwordx4 v[180:183], v[180:181], off offset:512 nt
	v_add_co_u32_e32 v184, vcc, 0x140000, v6
	s_nop 1
	v_addc_co_u32_e32 v185, vcc, 0, v7, vcc
	global_load_dwordx4 v[184:187], v[184:185], off offset:512 nt
	v_add_co_u32_e32 v188, vcc, 0x160000, v6
	s_nop 1
	v_addc_co_u32_e32 v189, vcc, 0, v7, vcc
	global_load_dwordx4 v[188:191], v[188:189], off offset:512 nt
	v_add_co_u32_e32 v192, vcc, 0x180000, v6
	s_nop 1
	v_addc_co_u32_e32 v193, vcc, 0, v7, vcc
	global_load_dwordx4 v[192:195], v[192:193], off offset:512 nt
	v_add_co_u32_e32 v196, vcc, 0x1a0000, v6
	s_nop 1
	v_addc_co_u32_e32 v197, vcc, 0, v7, vcc
	global_load_dwordx4 v[196:199], v[196:197], off offset:512 nt
	v_add_co_u32_e32 v200, vcc, 0x1c0000, v6
	s_nop 1
	v_addc_co_u32_e32 v201, vcc, 0, v7, vcc
	global_load_dwordx4 v[200:203], v[200:201], off offset:512 nt
	v_add_co_u32_e32 v204, vcc, 0x1e0000, v6
	s_nop 1
	v_addc_co_u32_e32 v205, vcc, 0, v7, vcc
	global_load_dwordx4 v[204:207], v[204:205], off offset:512 nt
	s_branch .LBB0_634
.LBB0_633:
	s_or_b64 exec, exec, s[60:61]
	s_waitcnt vmcnt(12)
	v_mov_b64_e32 v[24:25], v[160:161]
	v_mov_b64_e32 v[26:27], v[162:163]
	v_mov_b64_e32 v[244:245], v[164:165]
	v_mov_b64_e32 v[246:247], v[166:167]
	v_mov_b64_e32 v[248:249], v[168:169]
	v_mov_b64_e32 v[250:251], v[170:171]
	v_mov_b64_e32 v[252:253], v[172:173]
	v_mov_b64_e32 v[254:255], v[174:175]
	v_mov_b64_e32 v[160:161], v[176:177]
	v_mov_b64_e32 v[162:163], v[178:179]
	v_mov_b64_e32 v[164:165], v[180:181]
	v_mov_b64_e32 v[166:167], v[182:183]
	v_mov_b64_e32 v[168:169], v[184:185]
	v_mov_b64_e32 v[170:171], v[186:187]
	v_mov_b64_e32 v[172:173], v[188:189]
	v_mov_b64_e32 v[174:175], v[190:191]
	v_mov_b64_e32 v[176:177], v[192:193]
	v_mov_b64_e32 v[178:179], v[194:195]
	v_mov_b64_e32 v[180:181], v[196:197]
	v_mov_b64_e32 v[182:183], v[198:199]
	v_mov_b64_e32 v[184:185], v[200:201]
	v_mov_b64_e32 v[186:187], v[202:203]
	v_mov_b64_e32 v[188:189], v[204:205]
	v_mov_b64_e32 v[190:191], v[206:207]
	s_add_u32 s58, s58, 0x80000
	s_addc_u32 s59, s59, 0
	v_lshl_add_u64 v[4:5], v[4:5], 0, s[6:7]
	v_add_u32_e32 v18, 0x8800, v18
	s_cmp_lg_u32 s58, 0x200000
	v_lshl_add_u64 v[10:11], v[10:11], 0, s[56:57]
	s_cbranch_scc0 .LBB0_619
.LBB0_634:
	v_lshl_add_u64 v[16:17], v[6:7], 0, s[58:59]
	ds_read_b128 v[28:31], v18
	v_lshl_add_u64 v[14:15], v[8:9], 0, s[58:59]
	v_lshl_add_u64 v[12:13], s[72:73], 0, v[4:5]
	v_add_co_u32_e32 v32, vcc, s15, v12
	s_waitcnt vmcnt(15) lgkmcnt(0)
	v_pk_fma_f32 v[26:27], v[2:3], v[30:31], v[26:27]
	v_pk_fma_f32 v[24:25], v[0:1], v[28:29], v[24:25]
	global_store_dwordx4 v[14:15], v[24:27], off offset:512
	v_mul_f32_e32 v23, v19, v24
	v_mul_f32_e32 v28, v20, v25
	v_pk_mul_f32 v[24:25], v[24:25], v[24:25]
	v_mul_f32_e32 v29, v21, v26
	v_mul_f32_e32 v30, v22, v27
	v_pk_mul_f32 v[26:27], v[26:27], v[26:27]
	v_cvt_pk_bf16_f32 v28, v23, v28
	v_add_f32_e32 v23, v24, v25
	v_add_f32_e32 v23, v26, v23
	v_add_f32_e32 v23, v27, v23
	v_addc_co_u32_e32 v33, vcc, 0, v13, vcc
	s_nop 0
	v_add_f32_dpp v23, v23, v23 quad_perm:[1,0,3,2] row_mask:0xf bank_mask:0xf bound_ctrl:1
	v_cvt_pk_bf16_f32 v29, v29, v30
	global_store_dwordx2 v[32:33], v[28:29], off offset:256
	s_nop 0
	v_add_f32_dpp v23, v23, v23 quad_perm:[2,3,0,1] row_mask:0xf bank_mask:0xf bound_ctrl:1
	s_nop 1
	v_add_f32_dpp v23, v23, v23 row_half_mirror row_mask:0xf bank_mask:0xf bound_ctrl:1
	s_nop 1
	v_add_f32_dpp v23, v23, v23 row_mirror row_mask:0xf bank_mask:0xf bound_ctrl:1
	v_mov_b32_e32 v24, v23
	s_nop 1
	v_permlane16_swap_b32_e32 v23, v24
	s_and_saveexec_b64 s[60:61], s[4:5]
	s_cbranch_execz .LBB0_636
	v_lshl_add_u64 v[26:27], s[72:73], 0, v[10:11]
	v_add_f32_e32 v23, v23, v24
	global_store_dword v[26:27], v23, off offset:-2048
.LBB0_636:
	s_or_b64 exec, exec, s[60:61]
	ds_read_b128 v[28:31], v18 offset:8704
	s_nop 0
	v_add_co_u32_e32 v32, vcc, s22, v14
	s_waitcnt vmcnt(17) lgkmcnt(0)
	v_pk_fma_f32 v[246:247], v[2:3], v[30:31], v[246:247]
	v_addc_co_u32_e32 v33, vcc, 0, v15, vcc
	v_pk_fma_f32 v[244:245], v[0:1], v[28:29], v[244:245]
	global_store_dwordx4 v[32:33], v[244:247], off offset:512
	v_mul_f32_e32 v23, v19, v244
	v_mul_f32_e32 v28, v20, v245
	v_pk_mul_f32 v[244:245], v[244:245], v[244:245]
	v_mul_f32_e32 v29, v21, v246
	v_mul_f32_e32 v30, v22, v247
	v_pk_mul_f32 v[246:247], v[246:247], v[246:247]
	v_cvt_pk_bf16_f32 v28, v23, v28
	v_add_f32_e32 v23, v244, v245
	v_add_f32_e32 v23, v246, v23
	v_add_f32_e32 v23, v247, v23
	v_add_co_u32_e32 v34, vcc, s33, v12
	s_nop 0
	v_add_f32_dpp v23, v23, v23 quad_perm:[1,0,3,2] row_mask:0xf bank_mask:0xf bound_ctrl:1
	v_addc_co_u32_e32 v35, vcc, 0, v13, vcc
	s_nop 0
	v_add_f32_dpp v23, v23, v23 quad_perm:[2,3,0,1] row_mask:0xf bank_mask:0xf bound_ctrl:1
	v_cvt_pk_bf16_f32 v29, v29, v30
	global_store_dwordx2 v[34:35], v[28:29], off offset:256
	s_nop 0
	v_add_f32_dpp v23, v23, v23 row_half_mirror row_mask:0xf bank_mask:0xf bound_ctrl:1
	s_nop 1
	v_add_f32_dpp v23, v23, v23 row_mirror row_mask:0xf bank_mask:0xf bound_ctrl:1
	v_mov_b32_e32 v244, v23
	s_nop 1
	v_permlane16_swap_b32_e32 v23, v244
	s_and_saveexec_b64 s[60:61], s[4:5]
	s_cbranch_execz .LBB0_638
	v_lshl_add_u64 v[246:247], s[72:73], 0, v[10:11]
	v_add_f32_e32 v23, v23, v244
	global_store_dword v[246:247], v23, off offset:-1024
.LBB0_638:
	s_or_b64 exec, exec, s[60:61]
	ds_read_b128 v[28:31], v18 offset:17408
	s_nop 0
	v_add_co_u32_e32 v32, vcc, s80, v14
	s_waitcnt vmcnt(19) lgkmcnt(0)
	v_pk_fma_f32 v[250:251], v[2:3], v[30:31], v[250:251]
	v_addc_co_u32_e32 v33, vcc, 0, v15, vcc
	v_pk_fma_f32 v[248:249], v[0:1], v[28:29], v[248:249]
	global_store_dwordx4 v[32:33], v[248:251], off offset:512
	v_mul_f32_e32 v23, v19, v248
	v_mul_f32_e32 v28, v20, v249
	v_pk_mul_f32 v[248:249], v[248:249], v[248:249]
	v_mul_f32_e32 v29, v21, v250
	v_mul_f32_e32 v30, v22, v251
	v_pk_mul_f32 v[250:251], v[250:251], v[250:251]
	v_cvt_pk_bf16_f32 v28, v23, v28
	v_add_f32_e32 v23, v248, v249
	v_add_f32_e32 v23, v250, v23
	v_add_f32_e32 v23, v251, v23
	v_add_co_u32_e32 v34, vcc, s81, v12
	s_nop 0
	v_add_f32_dpp v23, v23, v23 quad_perm:[1,0,3,2] row_mask:0xf bank_mask:0xf bound_ctrl:1
	v_addc_co_u32_e32 v35, vcc, 0, v13, vcc
	s_nop 0
	v_add_f32_dpp v23, v23, v23 quad_perm:[2,3,0,1] row_mask:0xf bank_mask:0xf bound_ctrl:1
	v_cvt_pk_bf16_f32 v29, v29, v30
	global_store_dwordx2 v[34:35], v[28:29], off offset:256
	s_nop 0
	v_add_f32_dpp v23, v23, v23 row_half_mirror row_mask:0xf bank_mask:0xf bound_ctrl:1
	s_nop 1
	v_add_f32_dpp v23, v23, v23 row_mirror row_mask:0xf bank_mask:0xf bound_ctrl:1
	v_mov_b32_e32 v248, v23
	s_nop 1
	v_permlane16_swap_b32_e32 v23, v248
	s_and_saveexec_b64 s[60:61], s[4:5]
	s_cbranch_execz .LBB0_640
	v_lshl_add_u64 v[250:251], s[72:73], 0, v[10:11]
	v_add_f32_e32 v23, v23, v248
	global_store_dword v[250:251], v23, off
.LBB0_640:
	s_or_b64 exec, exec, s[60:61]
	ds_read_b128 v[28:31], v18 offset:26112
	s_nop 0
	v_add_co_u32_e32 v16, vcc, s82, v14
	s_nop 1
	v_addc_co_u32_e32 v17, vcc, 0, v15, vcc
	v_add_co_u32_e32 v32, vcc, s83, v12
	s_waitcnt vmcnt(21) lgkmcnt(0)
	v_pk_fma_f32 v[14:15], v[2:3], v[30:31], v[254:255]
	v_addc_co_u32_e32 v33, vcc, 0, v13, vcc
	v_pk_fma_f32 v[12:13], v[0:1], v[28:29], v[252:253]
	global_store_dwordx4 v[16:17], v[12:15], off offset:512
	v_mul_f32_e32 v16, v19, v12
	v_mul_f32_e32 v17, v20, v13
	v_pk_mul_f32 v[12:13], v[12:13], v[12:13]
	v_mul_f32_e32 v23, v21, v14
	v_mul_f32_e32 v252, v22, v15
	v_pk_mul_f32 v[14:15], v[14:15], v[14:15]
	v_add_f32_e32 v12, v12, v13
	v_add_f32_e32 v12, v14, v12
	v_add_f32_e32 v12, v15, v12
	v_cvt_pk_bf16_f32 v16, v16, v17
	v_cvt_pk_bf16_f32 v17, v23, v252
	global_store_dwordx2 v[32:33], v[16:17], off offset:256
	s_nop 0
	v_add_f32_dpp v12, v12, v12 quad_perm:[1,0,3,2] row_mask:0xf bank_mask:0xf bound_ctrl:1
	s_nop 1
	v_add_f32_dpp v12, v12, v12 quad_perm:[2,3,0,1] row_mask:0xf bank_mask:0xf bound_ctrl:1
	s_nop 1
	v_add_f32_dpp v12, v12, v12 row_half_mirror row_mask:0xf bank_mask:0xf bound_ctrl:1
	s_nop 1
	v_add_f32_dpp v12, v12, v12 row_mirror row_mask:0xf bank_mask:0xf bound_ctrl:1
	v_mov_b32_e32 v13, v12
	s_nop 1
	v_permlane16_swap_b32_e32 v12, v13
	s_and_saveexec_b64 s[60:61], s[4:5]
	s_cbranch_execz .LBB0_633
	v_lshl_add_u64 v[14:15], s[72:73], 0, v[10:11]
	v_add_f32_e32 v12, v12, v13
	global_store_dword v[14:15], v12, off offset:1024
	s_branch .LBB0_633
